# weight-conversion transpose read-back: LDS reads hoisted 3 waits ahead with counted waits (4 phase copies) + dead volatile LDS reads removed from the phase dispatch; on v30
# speedup vs baseline: 1.0222x; 1.0004x over previous
.Lnoperm:
	v_mov_b32_e32 v1, s54
	v_mov_b32_e32 v1, s54
	v_mov_b32_e32 v1, s54
	v_mov_b32_e32 v1, s54
	v_mov_b32_e32 v1, s54
	v_mov_b32_e32 v2, s54
	ds_read_b32 v1, v1 offset:148
	ds_read_b32 v2, v2 offset:144
	v_mov_b32_e32 v3, s54
	s_waitcnt vmcnt(0)
	v_mov_b32_e32 v4, s54
	s_add_u32 s68, s90, 0xa0000
	ds_read_b32 v3, v3 offset:156
	ds_read_b32 v4, v4 offset:152
	s_addc_u32 s69, s91, 0
	s_add_u32 s63, s90, 0x2a1000
	s_addc_u32 s76, s91, 0
	s_waitcnt lgkmcnt(0)
	v_readfirstlane_b32 s1, v1
	v_readfirstlane_b32 s0, v2
	s_add_u32 s96, s90, 0x3924000
	s_addc_u32 s97, s91, 0
	v_writelane_b32 v254, s0, 57
	s_add_u32 s92, s90, 0x5934000
	s_addc_u32 s93, s91, 0
	v_writelane_b32 v254, s1, 58
	v_readfirstlane_b32 s1, v3
	v_readfirstlane_b32 s0, v4
	s_movk_i32 s81, 0x3c4
	s_nop 0
	v_writelane_b32 v254, s0, 59
	s_nop 1
	v_writelane_b32 v254, s1, 60
	s_add_u32 s0, s90, 0x1424000
	s_addc_u32 s1, s91, 0
	v_writelane_b32 v254, s0, 61
	s_nop 1
	v_writelane_b32 v254, s1, 62
	s_add_u32 s0, s90, 0x24a4000
	s_addc_u32 s1, s91, 0
	v_writelane_b32 v254, s0, 63
	s_nop 1
	v_writelane_b32 v255, s1, 0
	s_add_i32 s0, s30, -1
	s_mul_hi_u32 s1, s0, 0x38e38e39
	s_lshr_b32 s8, s1, 1
	s_mul_i32 s33, s8, -9
	s_add_i32 s33, s33, s0
	s_cmp_gt_i32 s33, 1
	s_mul_i32 s77, s8, 3
	s_cselect_b64 s[0:1], -1, 0
	s_cmp_gt_i32 s33, 6
	s_cselect_b64 s[4:5], -1, 0
	s_bitcmp1_b32 s77, 0
	s_cselect_b64 s[6:7], -1, 0
	s_xor_b64 s[0:1], s[0:1], s[6:7]
	s_xor_b64 s[48:49], s[4:5], s[0:1]
	s_and_b64 s[0:1], s[48:49], exec
	s_mov_b32 s0, s8
	v_writelane_b32 v255, s0, 1
	s_mul_i32 s58, s8, 0x6e00
	s_cselect_b32 s95, s76, s69
	s_cselect_b32 s94, s63, s68
	v_writelane_b32 v255, s1, 2
	s_lshl_b64 s[0:1], s[58:59], 3
	s_add_u32 s0, s90, s0
	s_addc_u32 s1, s91, s1
	s_add_u32 s0, s0, 0x4000
	s_addc_u32 s1, s1, 0
	v_writelane_b32 v255, s0, 3
	s_cmp_lt_u32 s30, 10
	s_nop 0
	v_writelane_b32 v255, s1, 4
	s_cselect_b64 s[0:1], -1, 0
	v_writelane_b32 v255, s0, 5
	s_nop 1
	v_writelane_b32 v255, s1, 6
	s_and_b64 s[0:1], s[0:1], exec
	s_mov_b32 s0, 0x2a24000
	s_cselect_b32 s0, s0, 0x31a4000
	s_add_u32 s4, s90, s0
	s_addc_u32 s5, s91, 0
	s_add_u32 s0, s4, 0x580000
	v_writelane_b32 v255, s4, 7
	s_addc_u32 s1, s5, 0
	s_cmp_lt_i32 s33, 7
	v_writelane_b32 v255, s5, 8
	v_writelane_b32 v255, s0, 9
	s_nop 1
	v_writelane_b32 v255, s1, 10
	s_cbranch_scc1 .LBB0_362
	s_cmp_lg_u32 s33, 7
	s_mov_b64 s[0:1], -1
	s_cselect_b64 s[4:5], -1, 0
	s_cbranch_execz .LBB0_363
	s_branch .LBB0_364

.LBB0_622:
	s_or_b64 exec, exec, s[16:17]
	s_waitcnt lgkmcnt(0)
	ds_read_b32 v224, v114 offset:132
	ds_read_b32 v225, v114 offset:264
	ds_read_b32 v226, v114 offset:396
	ds_read_b32 v227, v114 offset:528
	ds_read_b32 v228, v114 offset:660
	ds_read_b32 v12, v114
	s_nop 0
	s_add_i32 s3, s7, s19
	s_ashr_i32 s15, s14, 31
	v_lshl_add_u64 v[16:17], s[14:15], 1, v[10:11]
	s_addk_i32 s7, 0x4000
	ds_read_b32 v229, v114 offset:792
	ds_read_b32 v230, v114 offset:924
	s_waitcnt lgkmcnt(2)
	v_cvt_pk_bf16_f32 v12, v12, v224
	s_nop 0
	s_nop 0
	ds_read_b32 v224, v114 offset:32
	ds_read_b32 v231, v114 offset:164
	s_waitcnt lgkmcnt(4)
	v_cvt_pk_bf16_f32 v13, v225, v226
	s_nop 0
	s_nop 0
	ds_read_b32 v225, v114 offset:296
	ds_read_b32 v226, v114 offset:428
	s_waitcnt lgkmcnt(6)
	v_cvt_pk_bf16_f32 v14, v227, v228
	s_nop 0
	s_nop 0
	ds_read_b32 v227, v114 offset:560
	ds_read_b32 v228, v114 offset:692
	s_waitcnt lgkmcnt(6)
	v_cvt_pk_bf16_f32 v15, v229, v230
	v_add_u32_e32 v18, s3, v78
	v_ashrrev_i32_e32 v19, 31, v18
	v_lshlrev_b64 v[20:21], 11, v[18:19]
	v_lshl_add_u64 v[20:21], v[16:17], 0, v[20:21]
	global_store_dwordx4 v[20:21], v[12:15], off
	s_nop 0
	s_nop 0
	v_add_u32_e32 v20, 8, v18
	v_ashrrev_i32_e32 v21, 31, v20
	v_lshlrev_b64 v[20:21], 11, v[20:21]
	v_lshl_add_u64 v[20:21], v[16:17], 0, v[20:21]
	ds_read_b32 v229, v114 offset:824
	ds_read_b32 v230, v114 offset:956
	s_waitcnt lgkmcnt(6)
	v_cvt_pk_bf16_f32 v12, v224, v231
	s_nop 0
	s_nop 0
	s_add_i32 s3, s18, 0x200
	s_cmpk_lt_i32 s18, 0x380
	s_mov_b32 s18, s3
	ds_read_b32 v224, v114 offset:64
	ds_read_b32 v231, v114 offset:196
	s_waitcnt lgkmcnt(6)
	v_cvt_pk_bf16_f32 v13, v225, v226
	s_nop 0
	s_nop 0
	ds_read_b32 v225, v114 offset:328
	ds_read_b32 v226, v114 offset:460
	s_waitcnt lgkmcnt(6)
	v_cvt_pk_bf16_f32 v14, v227, v228
	s_nop 0
	s_nop 0
	ds_read_b32 v227, v114 offset:592
	ds_read_b32 v228, v114 offset:724
	s_waitcnt lgkmcnt(6)
	v_cvt_pk_bf16_f32 v15, v229, v230
	global_store_dwordx4 v[20:21], v[12:15], off
	s_nop 0
	s_nop 0
	v_add_u32_e32 v20, 16, v18
	v_ashrrev_i32_e32 v21, 31, v20
	v_lshlrev_b64 v[20:21], 11, v[20:21]
	v_lshl_add_u64 v[20:21], v[16:17], 0, v[20:21]
	ds_read_b32 v229, v114 offset:856
	ds_read_b32 v230, v114 offset:988
	s_waitcnt lgkmcnt(6)
	v_cvt_pk_bf16_f32 v12, v224, v231
	s_nop 0
	s_nop 0
	v_add_u32_e32 v18, 24, v18
	ds_read_b32 v224, v114 offset:96
	ds_read_b32 v231, v114 offset:228
	s_waitcnt lgkmcnt(6)
	v_cvt_pk_bf16_f32 v13, v225, v226
	s_nop 0
	s_nop 0
	ds_read_b32 v225, v114 offset:360
	ds_read_b32 v226, v114 offset:492
	s_waitcnt lgkmcnt(6)
	v_cvt_pk_bf16_f32 v14, v227, v228
	s_nop 0
	s_nop 0
	ds_read_b32 v227, v114 offset:624
	ds_read_b32 v228, v114 offset:756
	s_waitcnt lgkmcnt(6)
	v_cvt_pk_bf16_f32 v15, v229, v230
	global_store_dwordx4 v[20:21], v[12:15], off
	s_nop 0
	s_nop 0
	ds_read_b32 v229, v114 offset:888
	ds_read_b32 v230, v114 offset:1020
	s_waitcnt lgkmcnt(6)
	v_cvt_pk_bf16_f32 v12, v224, v231
	s_nop 0
	s_nop 0
	s_waitcnt lgkmcnt(4)
	v_cvt_pk_bf16_f32 v13, v225, v226
	s_nop 0
	s_nop 0
	s_waitcnt lgkmcnt(2)
	v_cvt_pk_bf16_f32 v14, v227, v228
	s_nop 0
	s_nop 0
	s_waitcnt lgkmcnt(0)
	v_cvt_pk_bf16_f32 v15, v229, v230
	v_ashrrev_i32_e32 v19, 31, v18
	v_lshlrev_b64 v[18:19], 11, v[18:19]
	v_lshl_add_u64 v[16:17], v[16:17], 0, v[18:19]
	global_store_dwordx4 v[16:17], v[12:15], off
	s_waitcnt lgkmcnt(0)
	s_cbranch_scc0 .LBB0_696

.LBB0_959:
	s_or_b64 exec, exec, s[14:15]
	s_waitcnt lgkmcnt(0)
	ds_read_b32 v224, v111 offset:132
	ds_read_b32 v225, v111 offset:264
	ds_read_b32 v226, v111 offset:396
	ds_read_b32 v227, v111 offset:528
	ds_read_b32 v228, v111 offset:660
	ds_read_b32 v12, v111
	s_nop 0
	s_ashr_i32 s13, s12, 31
	v_lshl_add_u64 v[16:17], s[12:13], 1, v[10:11]
	s_add_i32 s0, s19, 0x400
	s_add_i32 s16, s16, 0x8000
	ds_read_b32 v229, v111 offset:792
	ds_read_b32 v230, v111 offset:924
	s_waitcnt lgkmcnt(2)
	v_cvt_pk_bf16_f32 v12, v12, v224
	s_nop 0
	s_nop 0
	s_addk_i32 s17, 0x4000
	s_cmpk_lt_i32 s19, 0x700
	s_mov_b32 s19, s0
	ds_read_b32 v224, v111 offset:32
	ds_read_b32 v231, v111 offset:164
	s_waitcnt lgkmcnt(4)
	v_cvt_pk_bf16_f32 v13, v225, v226
	s_nop 0
	s_nop 0
	ds_read_b32 v225, v111 offset:296
	ds_read_b32 v226, v111 offset:428
	s_waitcnt lgkmcnt(6)
	v_cvt_pk_bf16_f32 v14, v227, v228
	s_nop 0
	s_nop 0
	ds_read_b32 v227, v111 offset:560
	ds_read_b32 v228, v111 offset:692
	s_waitcnt lgkmcnt(6)
	v_cvt_pk_bf16_f32 v15, v229, v230
	v_add_u32_e32 v18, s10, v3
	v_ashrrev_i32_e32 v19, 31, v18
	v_lshlrev_b64 v[20:21], 11, v[18:19]
	v_lshl_add_u64 v[20:21], v[16:17], 0, v[20:21]
	global_store_dwordx4 v[20:21], v[12:15], off
	s_nop 0
	s_nop 0
	v_add_u32_e32 v20, 8, v18
	v_ashrrev_i32_e32 v21, 31, v20
	v_lshlrev_b64 v[20:21], 11, v[20:21]
	v_lshl_add_u64 v[20:21], v[16:17], 0, v[20:21]
	ds_read_b32 v229, v111 offset:824
	ds_read_b32 v230, v111 offset:956
	s_waitcnt lgkmcnt(6)
	v_cvt_pk_bf16_f32 v12, v224, v231
	s_nop 0
	s_nop 0
	ds_read_b32 v224, v111 offset:64
	ds_read_b32 v231, v111 offset:196
	s_waitcnt lgkmcnt(6)
	v_cvt_pk_bf16_f32 v13, v225, v226
	s_nop 0
	s_nop 0
	ds_read_b32 v225, v111 offset:328
	ds_read_b32 v226, v111 offset:460
	s_waitcnt lgkmcnt(6)
	v_cvt_pk_bf16_f32 v14, v227, v228
	s_nop 0
	s_nop 0
	ds_read_b32 v227, v111 offset:592
	ds_read_b32 v228, v111 offset:724
	s_waitcnt lgkmcnt(6)
	v_cvt_pk_bf16_f32 v15, v229, v230
	global_store_dwordx4 v[20:21], v[12:15], off
	s_nop 0
	s_nop 0
	v_add_u32_e32 v20, 16, v18
	v_ashrrev_i32_e32 v21, 31, v20
	v_lshlrev_b64 v[20:21], 11, v[20:21]
	v_lshl_add_u64 v[20:21], v[16:17], 0, v[20:21]
	ds_read_b32 v229, v111 offset:856
	ds_read_b32 v230, v111 offset:988
	s_waitcnt lgkmcnt(6)
	v_cvt_pk_bf16_f32 v12, v224, v231
	s_nop 0
	s_nop 0
	v_add_u32_e32 v18, 24, v18
	ds_read_b32 v224, v111 offset:96
	ds_read_b32 v231, v111 offset:228
	s_waitcnt lgkmcnt(6)
	v_cvt_pk_bf16_f32 v13, v225, v226
	s_nop 0
	s_nop 0
	ds_read_b32 v225, v111 offset:360
	ds_read_b32 v226, v111 offset:492
	s_waitcnt lgkmcnt(6)
	v_cvt_pk_bf16_f32 v14, v227, v228
	s_nop 0
	s_nop 0
	ds_read_b32 v227, v111 offset:624
	ds_read_b32 v228, v111 offset:756
	s_waitcnt lgkmcnt(6)
	v_cvt_pk_bf16_f32 v15, v229, v230
	global_store_dwordx4 v[20:21], v[12:15], off
	s_nop 0
	s_nop 0
	ds_read_b32 v229, v111 offset:888
	ds_read_b32 v230, v111 offset:1020
	s_waitcnt lgkmcnt(6)
	v_cvt_pk_bf16_f32 v12, v224, v231
	s_nop 0
	s_nop 0
	s_waitcnt lgkmcnt(4)
	v_cvt_pk_bf16_f32 v13, v225, v226
	s_nop 0
	s_nop 0
	s_waitcnt lgkmcnt(2)
	v_cvt_pk_bf16_f32 v14, v227, v228
	s_nop 0
	s_nop 0
	s_waitcnt lgkmcnt(0)
	v_cvt_pk_bf16_f32 v15, v229, v230
	v_ashrrev_i32_e32 v19, 31, v18
	v_lshlrev_b64 v[18:19], 11, v[18:19]
	v_lshl_add_u64 v[16:17], v[16:17], 0, v[18:19]
	global_store_dwordx4 v[16:17], v[12:15], off
	s_waitcnt lgkmcnt(0)
	s_cbranch_scc0 .LBB0_1028

.LBB0_1100:
	s_waitcnt lgkmcnt(0)
	ds_read_b32 v224, v3 offset:132
	ds_read_b32 v225, v3 offset:264
	ds_read_b32 v226, v3 offset:396
	ds_read_b32 v16, v3
	ds_read_b32 v227, v3 offset:528
	ds_read_b32 v228, v3 offset:660
	s_waitcnt lgkmcnt(2)
	s_nop 0
	s_waitcnt vmcnt(0)
	v_lshl_add_u64 v[56:57], s[12:13], 1, v[14:15]
	s_add_i32 s3, s21, 0x400
	s_add_i32 s19, s19, 0x8000
	s_addk_i32 s20, 0x4000
	ds_read_b32 v229, v3 offset:792
	ds_read_b32 v230, v3 offset:924
	s_waitcnt lgkmcnt(4)
	v_cvt_pk_bf16_f32 v16, v16, v224
	s_nop 0
	s_nop 0
	s_cmpk_lt_i32 s21, 0x700
	s_mov_b32 s21, s3
	ds_read_b32 v224, v3 offset:32
	ds_read_b32 v231, v3 offset:164
	s_waitcnt lgkmcnt(6)
	v_cvt_pk_bf16_f32 v17, v225, v226
	s_nop 0
	s_nop 0
	ds_read_b32 v225, v3 offset:296
	ds_read_b32 v226, v3 offset:428
	s_waitcnt lgkmcnt(6)
	v_cvt_pk_bf16_f32 v18, v227, v228
	s_nop 0
	s_nop 0
	ds_read_b32 v227, v3 offset:560
	ds_read_b32 v228, v3 offset:692
	s_waitcnt lgkmcnt(6)
	v_cvt_pk_bf16_f32 v19, v229, v230
	v_add_u32_e32 v58, s4, v1
	v_ashrrev_i32_e32 v59, 31, v58
	v_lshlrev_b64 v[60:61], 11, v[58:59]
	v_lshl_add_u64 v[60:61], v[56:57], 0, v[60:61]
	global_store_dwordx4 v[60:61], v[16:19], off
	s_nop 0
	s_nop 0
	v_add_u32_e32 v60, 8, v58
	v_ashrrev_i32_e32 v61, 31, v60
	v_lshlrev_b64 v[60:61], 11, v[60:61]
	v_lshl_add_u64 v[60:61], v[56:57], 0, v[60:61]
	ds_read_b32 v229, v3 offset:824
	ds_read_b32 v230, v3 offset:956
	s_waitcnt lgkmcnt(6)
	v_cvt_pk_bf16_f32 v16, v224, v231
	s_nop 0
	s_nop 0
	ds_read_b32 v224, v3 offset:64
	ds_read_b32 v231, v3 offset:196
	s_waitcnt lgkmcnt(6)
	v_cvt_pk_bf16_f32 v17, v225, v226
	s_nop 0
	s_nop 0
	ds_read_b32 v225, v3 offset:328
	ds_read_b32 v226, v3 offset:460
	s_waitcnt lgkmcnt(6)
	v_cvt_pk_bf16_f32 v18, v227, v228
	s_nop 0
	s_nop 0
	ds_read_b32 v227, v3 offset:592
	ds_read_b32 v228, v3 offset:724
	s_waitcnt lgkmcnt(6)
	v_cvt_pk_bf16_f32 v19, v229, v230
	global_store_dwordx4 v[60:61], v[16:19], off
	s_nop 0
	s_nop 0
	v_add_u32_e32 v60, 16, v58
	v_ashrrev_i32_e32 v61, 31, v60
	v_lshlrev_b64 v[60:61], 11, v[60:61]
	v_lshl_add_u64 v[60:61], v[56:57], 0, v[60:61]
	ds_read_b32 v229, v3 offset:856
	ds_read_b32 v230, v3 offset:988
	s_waitcnt lgkmcnt(6)
	v_cvt_pk_bf16_f32 v16, v224, v231
	s_nop 0
	s_nop 0
	v_add_u32_e32 v58, 24, v58
	ds_read_b32 v224, v3 offset:96
	ds_read_b32 v231, v3 offset:228
	s_waitcnt lgkmcnt(6)
	v_cvt_pk_bf16_f32 v17, v225, v226
	s_nop 0
	s_nop 0
	ds_read_b32 v225, v3 offset:360
	ds_read_b32 v226, v3 offset:492
	s_waitcnt lgkmcnt(6)
	v_cvt_pk_bf16_f32 v18, v227, v228
	s_nop 0
	s_nop 0
	ds_read_b32 v227, v3 offset:624
	ds_read_b32 v228, v3 offset:756
	s_waitcnt lgkmcnt(6)
	v_cvt_pk_bf16_f32 v19, v229, v230
	global_store_dwordx4 v[60:61], v[16:19], off
	s_nop 0
	s_nop 0
	ds_read_b32 v229, v3 offset:888
	ds_read_b32 v230, v3 offset:1020
	s_waitcnt lgkmcnt(6)
	v_cvt_pk_bf16_f32 v16, v224, v231
	s_nop 0
	s_nop 0
	s_waitcnt lgkmcnt(4)
	v_cvt_pk_bf16_f32 v17, v225, v226
	s_nop 0
	s_nop 0
	s_waitcnt lgkmcnt(2)
	v_cvt_pk_bf16_f32 v18, v227, v228
	s_nop 0
	s_nop 0
	s_waitcnt lgkmcnt(0)
	v_cvt_pk_bf16_f32 v19, v229, v230
	v_ashrrev_i32_e32 v59, 31, v58
	v_lshlrev_b64 v[58:59], 11, v[58:59]
	v_lshl_add_u64 v[56:57], v[56:57], 0, v[58:59]
	global_store_dwordx4 v[56:57], v[16:19], off
	s_waitcnt lgkmcnt(0)
	s_cbranch_scc0 .LBB0_1170

.LBB0_1241:
	s_waitcnt lgkmcnt(0)
	ds_read_b32 v224, v52 offset:132
	ds_read_b32 v225, v52 offset:264
	ds_read_b32 v226, v52 offset:396
	ds_read_b32 v14, v52
	ds_read_b32 v227, v52 offset:528
	ds_read_b32 v228, v52 offset:660
	s_waitcnt lgkmcnt(2)
	s_nop 0
	s_add_i32 s3, s12, s14
	s_waitcnt vmcnt(0)
	v_add_u32_e32 v56, s3, v1
	s_ashr_i32 s7, s6, 31
	v_ashrrev_i32_e32 v57, 31, v56
	ds_read_b32 v229, v52 offset:792
	ds_read_b32 v230, v52 offset:924
	s_waitcnt lgkmcnt(4)
	v_cvt_pk_bf16_f32 v14, v14, v224
	s_nop 0
	s_nop 0
	v_lshl_add_u64 v[54:55], s[6:7], 1, v[12:13]
	v_lshlrev_b64 v[58:59], 11, v[56:57]
	v_lshl_add_u64 v[58:59], v[54:55], 0, v[58:59]
	s_add_i32 s3, s13, 0x400
	ds_read_b32 v224, v52 offset:32
	ds_read_b32 v231, v52 offset:164
	s_waitcnt lgkmcnt(6)
	v_cvt_pk_bf16_f32 v15, v225, v226
	s_nop 0
	s_nop 0
	s_add_i32 s12, s12, 0x8000
	s_cmpk_lt_i32 s13, 0x180
	s_mov_b32 s13, s3
	ds_read_b32 v225, v52 offset:296
	ds_read_b32 v226, v52 offset:428
	s_waitcnt lgkmcnt(6)
	v_cvt_pk_bf16_f32 v16, v227, v228
	s_nop 0
	s_nop 0
	ds_read_b32 v227, v52 offset:560
	ds_read_b32 v228, v52 offset:692
	s_waitcnt lgkmcnt(6)
	v_cvt_pk_bf16_f32 v17, v229, v230
	global_store_dwordx4 v[58:59], v[14:17], off
	s_nop 0
	s_nop 0
	v_add_u32_e32 v58, 8, v56
	v_ashrrev_i32_e32 v59, 31, v58
	v_lshlrev_b64 v[58:59], 11, v[58:59]
	v_lshl_add_u64 v[58:59], v[54:55], 0, v[58:59]
	ds_read_b32 v229, v52 offset:824
	ds_read_b32 v230, v52 offset:956
	s_waitcnt lgkmcnt(6)
	v_cvt_pk_bf16_f32 v14, v224, v231
	s_nop 0
	s_nop 0
	ds_read_b32 v224, v52 offset:64
	ds_read_b32 v231, v52 offset:196
	s_waitcnt lgkmcnt(6)
	v_cvt_pk_bf16_f32 v15, v225, v226
	s_nop 0
	s_nop 0
	ds_read_b32 v225, v52 offset:328
	ds_read_b32 v226, v52 offset:460
	s_waitcnt lgkmcnt(6)
	v_cvt_pk_bf16_f32 v16, v227, v228
	s_nop 0
	s_nop 0
	ds_read_b32 v227, v52 offset:592
	ds_read_b32 v228, v52 offset:724
	s_waitcnt lgkmcnt(6)
	v_cvt_pk_bf16_f32 v17, v229, v230
	global_store_dwordx4 v[58:59], v[14:17], off
	s_nop 0
	s_nop 0
	v_add_u32_e32 v58, 16, v56
	v_ashrrev_i32_e32 v59, 31, v58
	v_lshlrev_b64 v[58:59], 11, v[58:59]
	v_lshl_add_u64 v[58:59], v[54:55], 0, v[58:59]
	ds_read_b32 v229, v52 offset:856
	ds_read_b32 v230, v52 offset:988
	s_waitcnt lgkmcnt(6)
	v_cvt_pk_bf16_f32 v14, v224, v231
	s_nop 0
	s_nop 0
	v_add_u32_e32 v56, 24, v56
	v_ashrrev_i32_e32 v57, 31, v56
	v_lshlrev_b64 v[56:57], 11, v[56:57]
	v_lshl_add_u64 v[54:55], v[54:55], 0, v[56:57]
	ds_read_b32 v224, v52 offset:96
	ds_read_b32 v231, v52 offset:228
	s_waitcnt lgkmcnt(6)
	v_cvt_pk_bf16_f32 v15, v225, v226
	s_nop 0
	s_nop 0
	ds_read_b32 v225, v52 offset:360
	ds_read_b32 v226, v52 offset:492
	s_waitcnt lgkmcnt(6)
	v_cvt_pk_bf16_f32 v16, v227, v228
	s_nop 0
	s_nop 0
	ds_read_b32 v227, v52 offset:624
	ds_read_b32 v228, v52 offset:756
	s_waitcnt lgkmcnt(6)
	v_cvt_pk_bf16_f32 v17, v229, v230
	global_store_dwordx4 v[58:59], v[14:17], off
	s_nop 0
	s_nop 0
	ds_read_b32 v229, v52 offset:888
	s_waitcnt lgkmcnt(5)
	v_cvt_pk_bf16_f32 v14, v224, v231
	s_nop 0
	s_nop 0
	s_waitcnt lgkmcnt(3)
	v_cvt_pk_bf16_f32 v15, v225, v226
	s_nop 0
	s_nop 0
	s_waitcnt lgkmcnt(1)
	v_cvt_pk_bf16_f32 v16, v227, v228
	s_nop 0
	ds_read_b32 v53, v52 offset:1020
	s_waitcnt lgkmcnt(0)
	v_cvt_pk_bf16_f32 v17, v229, v53
	global_store_dwordx4 v[54:55], v[14:17], off
	s_waitcnt lgkmcnt(0)
	s_cbranch_scc0 .LBB0_1316
